# up->down transitions (both layers): the down GEMM's first four weight-tile LDS-DMA loads are issued before the 4-workgroup sync's poll instead of after it
# speedup vs baseline: 1.0034x; 1.0034x over previous
.LBB0_667:
	s_waitcnt vmcnt(0)
	s_barrier
	s_waitcnt vmcnt(0)
	s_barrier
	v_readfirstlane_b32 s101, v226
	s_lshr_b32 s101, s101, 6
	s_lshl_b32 s101, s101, 10
	s_add_u32 s98, s96, s48
	s_addc_u32 s99, s97, 0
	s_add_u32 s98, s98, 0x1900000
	s_addc_u32 s99, s99, 0
	v_lshl_or_b32 v132, v190, 13, v188
	v_lshl_or_b32 v128, v187, 13, v188
	s_add_i32 m0, s101, 0x10000
	s_nop 0
	global_load_lds_dwordx4 v132, s[98:99]
	s_add_i32 m0, s101, 0x12000
	s_nop 0
	global_load_lds_dwordx4 v128, s[98:99]
	s_add_u32 s98, s98, 0x100000
	s_addc_u32 s99, s99, 0
	s_add_i32 m0, s101, 0x14000
	s_nop 0
	global_load_lds_dwordx4 v132, s[98:99]
	s_add_i32 m0, s101, 0x16000
	s_nop 0
	global_load_lds_dwordx4 v128, s[98:99]
	s_mov_b64 s[0:1], exec
	v_readlane_b32 s2, v254, 29
	v_readlane_b32 s3, v254, 30
	s_and_b64 s[2:3], s[0:1], s[2:3]
	s_mov_b64 exec, s[2:3]
	s_cbranch_execz .LBB0_681
	s_andn2_b64 vcc, exec, s[42:43]
	s_cbranch_vccnz .LBB0_670
	buffer_wbl2 sc1
	s_waitcnt vmcnt(0)
	s_waitcnt vmcnt(0)

.LBB0_681:
	s_or_b64 exec, exec, s[0:1]
	v_readfirstlane_b32 s18, v226
	s_lshr_b32 s6, s18, 6
	s_lshr_b32 s7, s18, 8
	s_lshl_b32 s16, s6, 10
	s_lshl_b64 s[2:3], s[40:41], 21
	s_add_u32 s12, s96, s48
	s_addc_u32 s13, s97, 0
	s_add_u32 s0, s12, 0x1900000
	s_addc_u32 s1, s13, 0
	s_add_i32 s19, s16, 0
	v_lshl_or_b32 v132, v190, 13, v188
	s_add_i32 m0, s19, 0x10000
	s_barrier
	s_add_i32 m0, s19, 0x12000
	v_lshl_or_b32 v128, v187, 13, v188
	s_add_u32 s12, s12, 0x1a00000
	s_addc_u32 s13, s13, 0
	s_add_i32 m0, s19, 0x14000
	v_lshl_or_b32 v134, v191, 13, v188
	s_add_i32 m0, s19, 0x16000
	s_add_u32 s2, s14, s2
	s_addc_u32 s3, s15, s3
	s_add_i32 s20, s19, 0x2000
	s_mov_b32 m0, s19
	s_add_u32 s12, s2, 0x100000
	v_lshl_or_b32 v130, v189, 13, v188
	global_load_lds_dwordx4 v134, s[2:3]
	s_mov_b32 m0, s20
	s_addc_u32 s13, s3, 0
	s_add_i32 s21, s19, 0x4000
	global_load_lds_dwordx4 v130, s[2:3]
	s_mov_b32 m0, s21
	s_add_i32 s22, s19, 0x6000
	global_load_lds_dwordx4 v134, s[12:13]
	s_mov_b32 m0, s22
	v_mov_b32_e32 v133, 0
	global_load_lds_dwordx4 v130, s[12:13]
	v_mov_b32_e32 v129, v133
	v_mov_b32_e32 v135, v133
	v_mov_b32_e32 v131, v133
	s_mov_b32 s13, 0
	v_lshl_add_u64 v[6:7], s[0:1], 0, v[132:133]
	v_lshl_add_u64 v[4:5], s[0:1], 0, v[128:129]
	v_lshl_add_u64 v[2:3], s[2:3], 0, v[134:135]
	s_cmp_lg_u32 s7, 1
	v_lshl_add_u64 v[0:1], s[2:3], 0, v[130:131]
	s_cbranch_scc1 .LBB0_683
	s_barrier

.LBB0_1000:
	s_waitcnt vmcnt(0)
	s_barrier
	s_waitcnt vmcnt(0)
	s_barrier
	v_readfirstlane_b32 s101, v226
	s_lshr_b32 s101, s101, 6
	s_lshl_b32 s101, s101, 10
	s_add_u32 s98, s96, s54
	s_addc_u32 s99, s97, 0
	s_add_u32 s98, s98, 0x2100000
	s_addc_u32 s99, s99, 0
	v_lshl_or_b32 v132, v189, 13, v187
	v_lshl_or_b32 v128, v186, 13, v187
	s_add_i32 m0, s101, 0x10000
	s_nop 0
	global_load_lds_dwordx4 v132, s[98:99]
	s_add_i32 m0, s101, 0x12000
	s_nop 0
	global_load_lds_dwordx4 v128, s[98:99]
	s_add_u32 s98, s98, 0x100000
	s_addc_u32 s99, s99, 0
	s_add_i32 m0, s101, 0x14000
	s_nop 0
	global_load_lds_dwordx4 v132, s[98:99]
	s_add_i32 m0, s101, 0x16000
	s_nop 0
	global_load_lds_dwordx4 v128, s[98:99]
	s_mov_b64 s[0:1], exec
	v_readlane_b32 s4, v254, 29
	v_readlane_b32 s5, v254, 30
	s_and_b64 s[4:5], s[0:1], s[4:5]
	s_mov_b64 exec, s[4:5]
	s_cbranch_execz .LBB0_1014
	s_and_b64 vcc, exec, s[2:3]
	s_cbranch_vccnz .LBB0_1003
	buffer_wbl2 sc1
	s_waitcnt vmcnt(0)
	s_waitcnt vmcnt(0)

.LBB0_1014:
	s_or_b64 exec, exec, s[0:1]
	v_readfirstlane_b32 s16, v226
	s_lshr_b32 s4, s16, 6
	s_lshr_b32 s5, s16, 8
	s_lshl_b32 s37, s4, 10
	s_add_u32 s2, s96, s54
	s_addc_u32 s3, s97, 0
	s_add_u32 s0, s2, 0x2100000
	s_addc_u32 s1, s3, 0
	s_add_i32 s17, s37, 0
	v_lshl_or_b32 v132, v189, 13, v187
	s_add_i32 m0, s17, 0x10000
	s_barrier
	s_add_i32 m0, s17, 0x12000
	v_lshl_or_b32 v128, v186, 13, v187
	s_add_u32 s2, s2, 0x2200000
	s_addc_u32 s3, s3, 0
	s_add_i32 m0, s17, 0x14000
	v_lshl_or_b32 v134, v190, 13, v187
	s_add_i32 m0, s17, 0x16000
	v_lshl_or_b32 v130, v188, 13, v187
	s_add_u32 s2, s14, s12
	s_addc_u32 s3, s15, s13
	s_add_i32 s18, s17, 0x2000
	s_mov_b32 m0, s17
	s_add_u32 s10, s2, 0x100000
	global_load_lds_dwordx4 v134, s[2:3]
	s_mov_b32 m0, s18
	s_addc_u32 s11, s3, 0
	s_add_i32 s19, s17, 0x4000
	global_load_lds_dwordx4 v130, s[2:3]
	s_mov_b32 m0, s19
	s_add_i32 s20, s17, 0x6000
	global_load_lds_dwordx4 v134, s[10:11]
	s_mov_b32 m0, s20
	v_mov_b32_e32 v133, 0
	global_load_lds_dwordx4 v130, s[10:11]
	v_mov_b32_e32 v129, v133
	v_mov_b32_e32 v135, v133
	v_mov_b32_e32 v131, v133
	v_lshl_add_u64 v[6:7], s[0:1], 0, v[132:133]
	v_lshl_add_u64 v[4:5], s[0:1], 0, v[128:129]
	v_lshl_add_u64 v[2:3], s[2:3], 0, v[134:135]
	s_cmp_lg_u32 s5, 1
	v_lshl_add_u64 v[0:1], s[2:3], 0, v[130:131]
	s_cbranch_scc1 .LBB0_1016
	s_barrier
